# hardened configuration, local-barrier arrival spin without s_sleep (back-to-back polls)
# speedup vs baseline: 1.0047x; 1.0047x over previous
; __device__ __forceinline__ unsigned xb_ld(unsigned* p)              { return __hip_atomic_load(p, __ATOMIC_RELAXED, __HIP_MEMORY_SCOPE_AGENT); }
; #define XB_SPIN(cond, bar) do { unsigned _sp = 0; while (cond) { __builtin_amdgcn_s_sleep(1); \
;     if ((++_sp & 255u) == 0u) { if (xb_ld(&(bar)[XB_TMO])) break; if (_sp > XB_SPIN_CAP) { atomicAdd(&(bar)[XB_TMO], 1u); break; } } } } while (0)
; __device__ __forceinline__ void xcd_barrier(const XcdBarrier& b) {
;     ...
;             XB_SPIN(xb_ld(&bar[XB_XGEN(b.x)]) == gen, bar);
cvx_spin:
	global_load_dword v0, v3, s[22:23] sc1
	s_waitcnt vmcnt(0)
	v_readfirstlane_b32 s34, v0
	s_nop 0
	s_cmp_ge_u32 s34, s3
	s_cbranch_scc1 cvx_arrived
	s_add_i32 s2, s2, 1
	s_cmp_lt_u32 s2, 0x100000
	s_cbranch_scc1 cvx_spin
